# GEMM phases: per-tile accumulator zeroing with v_mov_b64 (half the VALU slots between tiles)
# baseline (speedup 1.0000x reference)
; template <class Epi, class Sched>
; __device__ __forceinline__ void gemm_phase(LAS unsigned char* lds, const Gemm g, const Sched& S, const Epi& E, const int tid) {
;     ...
;         const char* nA = has_next ? (const char*)g.A + (size_t)nxt.pm * tstep + (size_t)nxt.koff * 2 : cA; const char* nB = has_next ? (const char*)g.Bt + (size_t)nxt.pn * tstep + (size_t)nxt.koff * 2 : cB;
;     ...
;         if (!(Epi::CHAIN && nxt.seg != 0))
; #pragma unroll
;         for (int a = 0; a < 2; ++a)
; #pragma unroll
;             for (int b = 0; b < 2; ++b)
; #pragma unroll
;                 for (int m = 0; m < 4; ++m)
; #pragma unroll
;                     for (int n = 0; n < 2; ++n) acc[a][b][m][n] = (f32x4){0.f, 0.f, 0.f, 0.f};
;         cur = nxt; cA = nA; cB = nB; ++ui;
.LBB0_29:
	s_ashr_i32 s23, s22, 31
	s_lshl_b64 s[26:27], s[22:23], 19
	s_add_u32 s48, s21, s26
	s_addc_u32 s49, s36, s27
	s_and_b64 s[26:27], s[6:7], exec
	s_cselect_b32 s23, s49, s55
	s_cselect_b32 s70, s48, s54
	s_ashr_i32 s19, s18, 31
	s_lshl_b64 s[26:27], s[18:19], 19
	s_add_u32 s50, s42, s26
	s_addc_u32 s51, s43, s27
	s_and_b64 s[26:27], s[6:7], exec
	s_cselect_b32 s19, s51, s57
	s_cselect_b32 s71, s50, s56
	s_add_u32 s54, s54, 0x40080
	s_addc_u32 s55, s55, 0
	s_add_u32 s76, s56, 0x100
	v_mov_b64_e32 v[2:3], 0
	s_addc_u32 s79, s57, 0
	s_mov_b32 s72, -2
	v_mov_b64_e32 v[4:5], 0
	v_mov_b64_e32 v[6:7], 0
	v_mov_b64_e32 v[8:9], 0
	v_mov_b64_e32 v[14:15], 0
	v_mov_b64_e32 v[16:17], 0
	v_mov_b64_e32 v[22:23], 0
	v_mov_b64_e32 v[24:25], 0
	v_mov_b64_e32 v[30:31], 0
	v_mov_b64_e32 v[32:33], 0
	v_mov_b64_e32 v[38:39], 0
	v_mov_b64_e32 v[40:41], 0
	v_mov_b64_e32 v[46:47], 0
	v_mov_b64_e32 v[48:49], 0
	v_mov_b64_e32 v[54:55], 0
	v_mov_b64_e32 v[56:57], 0
	v_mov_b64_e32 v[10:11], 0
	v_mov_b64_e32 v[12:13], 0
	v_mov_b64_e32 v[18:19], 0
	v_mov_b64_e32 v[20:21], 0
	v_mov_b64_e32 v[26:27], 0
	v_mov_b64_e32 v[28:29], 0
	v_mov_b64_e32 v[34:35], 0
	v_mov_b64_e32 v[36:37], 0
	v_mov_b64_e32 v[42:43], 0
	v_mov_b64_e32 v[44:45], 0
	v_mov_b64_e32 v[50:51], 0
	v_mov_b64_e32 v[52:53], 0
	v_mov_b64_e32 v[58:59], 0
	v_mov_b64_e32 v[60:61], 0
	v_mov_b64_e32 v[62:63], 0
	v_mov_b64_e32 v[64:65], 0
	v_mov_b64_e32 v[66:67], 0
	v_mov_b64_e32 v[68:69], 0
	v_mov_b64_e32 v[70:71], 0
	v_mov_b64_e32 v[72:73], 0
	v_mov_b64_e32 v[78:79], 0
	v_mov_b64_e32 v[80:81], 0
	s_waitcnt vmcnt(0)
	v_mov_b64_e32 v[86:87], 0
	v_mov_b64_e32 v[88:89], 0
	v_mov_b64_e32 v[94:95], 0
	v_mov_b64_e32 v[96:97], 0
	v_mov_b64_e32 v[102:103], 0
	v_mov_b64_e32 v[104:105], 0
	v_mov_b64_e32 v[110:111], 0
	v_mov_b64_e32 v[112:113], 0
	v_mov_b64_e32 v[118:119], 0
	v_mov_b64_e32 v[120:121], 0
	v_mov_b64_e32 v[74:75], 0
	v_mov_b64_e32 v[76:77], 0
	v_mov_b64_e32 v[82:83], 0
	v_mov_b64_e32 v[84:85], 0
	v_mov_b64_e32 v[90:91], 0
	v_mov_b64_e32 v[92:93], 0
	v_mov_b64_e32 v[98:99], 0
	v_mov_b64_e32 v[100:101], 0
	v_mov_b64_e32 v[106:107], 0
	v_mov_b64_e32 v[108:109], 0
	v_mov_b64_e32 v[114:115], 0
	v_mov_b64_e32 v[116:117], 0
	v_mov_b64_e32 v[122:123], 0
	v_mov_b64_e32 v[124:125], 0
	v_mov_b64_e32 v[126:127], 0
	v_mov_b64_e32 v[128:129], 0

; template <class Epi, class Sched>
; __device__ __forceinline__ void gemm_phase(LAS unsigned char* lds, const Gemm g, const Sched& S, const Epi& E, const int tid) {
;     ...
;         const char* nA = has_next ? (const char*)g.A + (size_t)nxt.pm * tstep + (size_t)nxt.koff * 2 : cA; const char* nB = has_next ? (const char*)g.Bt + (size_t)nxt.pn * tstep + (size_t)nxt.koff * 2 : cB;
;     ...
;         if (!(Epi::CHAIN && nxt.seg != 0))
; #pragma unroll
;         for (int a = 0; a < 2; ++a)
; #pragma unroll
;             for (int b = 0; b < 2; ++b)
; #pragma unroll
;                 for (int m = 0; m < 4; ++m)
; #pragma unroll
;                     for (int n = 0; n < 2; ++n) acc[a][b][m][n] = (f32x4){0.f, 0.f, 0.f, 0.f};
;         cur = nxt; cA = nA; cB = nB; ++ui;
.LBB0_60:
	s_ashr_i32 s55, s54, 31
	s_lshl_b64 s[26:27], s[54:55], 19
	s_add_u32 s28, s11, s26
	s_addc_u32 s30, s21, s27
	s_and_b64 s[26:27], s[6:7], exec
	s_cselect_b32 s57, s30, s65
	s_cselect_b32 s56, s28, s64
	s_ashr_i32 s53, s52, 31
	s_lshl_b64 s[26:27], s[52:53], 19
	s_add_u32 s28, s36, s26
	s_addc_u32 s30, s42, s27
	s_and_b64 s[26:27], s[6:7], exec
	s_cselect_b32 s59, s30, s67
	s_cselect_b32 s58, s28, s66
	s_add_u32 s28, s66, 0x100
	v_mov_b64_e32 v[2:3], 0
	s_addc_u32 s53, s67, 0
	s_mov_b32 s55, -2
	s_waitcnt lgkmcnt(0)
	v_mov_b64_e32 v[4:5], 0
	v_mov_b64_e32 v[6:7], 0
	v_mov_b64_e32 v[8:9], 0
	v_mov_b64_e32 v[18:19], 0
	v_mov_b64_e32 v[20:21], 0
	v_mov_b64_e32 v[22:23], 0
	v_mov_b64_e32 v[24:25], 0
	v_mov_b64_e32 v[34:35], 0
	v_mov_b64_e32 v[36:37], 0
	v_mov_b64_e32 v[38:39], 0
	v_mov_b64_e32 v[40:41], 0
	v_mov_b64_e32 v[50:51], 0
	v_mov_b64_e32 v[52:53], 0
	v_mov_b64_e32 v[54:55], 0
	v_mov_b64_e32 v[56:57], 0
	v_mov_b64_e32 v[10:11], 0
	v_mov_b64_e32 v[12:13], 0
	v_mov_b64_e32 v[14:15], 0
	v_mov_b64_e32 v[16:17], 0
	v_mov_b64_e32 v[26:27], 0
	v_mov_b64_e32 v[28:29], 0
	v_mov_b64_e32 v[30:31], 0
	v_mov_b64_e32 v[32:33], 0
	v_mov_b64_e32 v[42:43], 0
	v_mov_b64_e32 v[44:45], 0
	v_mov_b64_e32 v[46:47], 0
	v_mov_b64_e32 v[48:49], 0
	v_mov_b64_e32 v[58:59], 0
	v_mov_b64_e32 v[60:61], 0
	v_mov_b64_e32 v[62:63], 0
	v_mov_b64_e32 v[64:65], 0
	v_mov_b64_e32 v[66:67], 0
	v_mov_b64_e32 v[68:69], 0
	v_mov_b64_e32 v[70:71], 0
	v_mov_b64_e32 v[72:73], 0
	v_mov_b64_e32 v[82:83], 0
	v_mov_b64_e32 v[84:85], 0
	s_waitcnt vmcnt(0)
	v_mov_b64_e32 v[86:87], 0
	v_mov_b64_e32 v[88:89], 0
	v_mov_b64_e32 v[98:99], 0
	v_mov_b64_e32 v[100:101], 0
	v_mov_b64_e32 v[102:103], 0
	v_mov_b64_e32 v[104:105], 0
	v_mov_b64_e32 v[114:115], 0
	v_mov_b64_e32 v[116:117], 0
	v_mov_b64_e32 v[118:119], 0
	v_mov_b64_e32 v[120:121], 0
	v_mov_b64_e32 v[74:75], 0
	v_mov_b64_e32 v[76:77], 0
	v_mov_b64_e32 v[78:79], 0
	v_mov_b64_e32 v[80:81], 0
	v_mov_b64_e32 v[90:91], 0
	v_mov_b64_e32 v[92:93], 0
	v_mov_b64_e32 v[94:95], 0
	v_mov_b64_e32 v[96:97], 0
	v_mov_b64_e32 v[106:107], 0
	v_mov_b64_e32 v[108:109], 0
	v_mov_b64_e32 v[110:111], 0
	v_mov_b64_e32 v[112:113], 0
	v_mov_b64_e32 v[122:123], 0
	v_mov_b64_e32 v[124:125], 0
	v_mov_b64_e32 v[126:127], 0
	v_mov_b64_e32 v[128:129], 0

; template <class Epi, class Sched>
; __device__ __forceinline__ void gemm_phase(LAS unsigned char* lds, const Gemm g, const Sched& S, const Epi& E, const int tid) {
;     ...
;         const char* nA = has_next ? (const char*)g.A + (size_t)nxt.pm * tstep + (size_t)nxt.koff * 2 : cA; const char* nB = has_next ? (const char*)g.Bt + (size_t)nxt.pn * tstep + (size_t)nxt.koff * 2 : cB;
;     ...
;         if (!(Epi::CHAIN && nxt.seg != 0))
; #pragma unroll
;         for (int a = 0; a < 2; ++a)
; #pragma unroll
;             for (int b = 0; b < 2; ++b)
; #pragma unroll
;                 for (int m = 0; m < 4; ++m)
; #pragma unroll
;                     for (int n = 0; n < 2; ++n) acc[a][b][m][n] = (f32x4){0.f, 0.f, 0.f, 0.f};
;         cur = nxt; cA = nA; cB = nB; ++ui;
.LBB0_238:
	s_ashr_i32 s57, s56, 31
	s_lshl_b64 s[58:59], s[56:57], 19
	s_add_u32 s58, s71, s58
	s_addc_u32 s59, s36, s59
	s_and_b64 s[60:61], s[6:7], exec
	s_cselect_b32 s28, s59, s63
	s_cselect_b32 s57, s58, s62
	s_ashr_i32 s55, s54, 31
	s_lshl_b64 s[60:61], s[54:55], 19
	s_add_u32 s60, s86, s60
	s_addc_u32 s61, s42, s61
	s_and_b64 s[68:69], s[6:7], exec
	s_cselect_b32 s55, s61, s65
	s_cselect_b32 s67, s60, s64
	s_add_u32 s62, s62, 0x40080
	s_addc_u32 s63, s63, 0
	s_add_u32 vcc_lo, s64, 0x100
	v_mov_b64_e32 v[2:3], 0
	s_addc_u32 vcc_hi, s65, 0
	s_mov_b32 s72, -2
	v_mov_b64_e32 v[4:5], 0
	v_mov_b64_e32 v[6:7], 0
	v_mov_b64_e32 v[8:9], 0
	v_mov_b64_e32 v[18:19], 0
	v_mov_b64_e32 v[20:21], 0
	v_mov_b64_e32 v[22:23], 0
	v_mov_b64_e32 v[24:25], 0
	v_mov_b64_e32 v[34:35], 0
	v_mov_b64_e32 v[36:37], 0
	v_mov_b64_e32 v[38:39], 0
	v_mov_b64_e32 v[40:41], 0
	v_mov_b64_e32 v[50:51], 0
	v_mov_b64_e32 v[52:53], 0
	v_mov_b64_e32 v[54:55], 0
	v_mov_b64_e32 v[56:57], 0
	v_mov_b64_e32 v[10:11], 0
	v_mov_b64_e32 v[12:13], 0
	v_mov_b64_e32 v[14:15], 0
	v_mov_b64_e32 v[16:17], 0
	v_mov_b64_e32 v[26:27], 0
	v_mov_b64_e32 v[28:29], 0
	v_mov_b64_e32 v[30:31], 0
	v_mov_b64_e32 v[32:33], 0
	v_mov_b64_e32 v[42:43], 0
	v_mov_b64_e32 v[44:45], 0
	v_mov_b64_e32 v[46:47], 0
	v_mov_b64_e32 v[48:49], 0
	v_mov_b64_e32 v[58:59], 0
	v_mov_b64_e32 v[60:61], 0
	v_mov_b64_e32 v[62:63], 0
	v_mov_b64_e32 v[64:65], 0
	v_mov_b64_e32 v[66:67], 0
	v_mov_b64_e32 v[68:69], 0
	v_mov_b64_e32 v[70:71], 0
	v_mov_b64_e32 v[72:73], 0
	v_mov_b64_e32 v[82:83], 0
	v_mov_b64_e32 v[84:85], 0
	s_waitcnt vmcnt(0)
	v_mov_b64_e32 v[86:87], 0
	v_mov_b64_e32 v[88:89], 0
	v_mov_b64_e32 v[98:99], 0
	v_mov_b64_e32 v[100:101], 0
	v_mov_b64_e32 v[102:103], 0
	v_mov_b64_e32 v[104:105], 0
	v_mov_b64_e32 v[114:115], 0
	v_mov_b64_e32 v[116:117], 0
	v_mov_b64_e32 v[118:119], 0
	v_mov_b64_e32 v[120:121], 0
	v_mov_b64_e32 v[74:75], 0
	v_mov_b64_e32 v[76:77], 0
	v_mov_b64_e32 v[78:79], 0
	v_mov_b64_e32 v[80:81], 0
	v_mov_b64_e32 v[90:91], 0
	v_mov_b64_e32 v[92:93], 0
	v_mov_b64_e32 v[94:95], 0
	v_mov_b64_e32 v[96:97], 0
	v_mov_b64_e32 v[106:107], 0
	v_mov_b64_e32 v[108:109], 0
	v_mov_b64_e32 v[110:111], 0
	v_mov_b64_e32 v[112:113], 0
	v_mov_b64_e32 v[122:123], 0
	v_mov_b64_e32 v[124:125], 0
	v_mov_b64_e32 v[126:127], 0
	v_mov_b64_e32 v[128:129], 0

; template <class Epi, class Sched>
; __device__ __forceinline__ void gemm_phase(LAS unsigned char* lds, const Gemm g, const Sched& S, const Epi& E, const int tid) {
;     ...
;         const char* nA = has_next ? (const char*)g.A + (size_t)nxt.pm * tstep + (size_t)nxt.koff * 2 : cA; const char* nB = has_next ? (const char*)g.Bt + (size_t)nxt.pn * tstep + (size_t)nxt.koff * 2 : cB;
;     ...
;         if (!(Epi::CHAIN && nxt.seg != 0))
; #pragma unroll
;         for (int a = 0; a < 2; ++a)
; #pragma unroll
;             for (int b = 0; b < 2; ++b)
; #pragma unroll
;                 for (int m = 0; m < 4; ++m)
; #pragma unroll
;                     for (int n = 0; n < 2; ++n) acc[a][b][m][n] = (f32x4){0.f, 0.f, 0.f, 0.f};
;         cur = nxt; cA = nA; cB = nB; ++ui;
.LBB0_417:
	s_add_u32 s69, s52, 0x100
	v_mov_b64_e32 v[2:3], 0
	s_addc_u32 s70, s53, 0
	s_mov_b32 s71, -2
	s_waitcnt lgkmcnt(0)
	v_mov_b64_e32 v[4:5], 0
	v_mov_b64_e32 v[6:7], 0
	v_mov_b64_e32 v[8:9], 0
	v_mov_b64_e32 v[18:19], 0
	v_mov_b64_e32 v[20:21], 0
	v_mov_b64_e32 v[22:23], 0
	v_mov_b64_e32 v[24:25], 0
	v_mov_b64_e32 v[34:35], 0
	v_mov_b64_e32 v[36:37], 0
	v_mov_b64_e32 v[38:39], 0
	v_mov_b64_e32 v[40:41], 0
	v_mov_b64_e32 v[50:51], 0
	v_mov_b64_e32 v[52:53], 0
	v_mov_b64_e32 v[54:55], 0
	v_mov_b64_e32 v[56:57], 0
	v_mov_b64_e32 v[10:11], 0
	v_mov_b64_e32 v[12:13], 0
	v_mov_b64_e32 v[14:15], 0
	v_mov_b64_e32 v[16:17], 0
	v_mov_b64_e32 v[26:27], 0
	v_mov_b64_e32 v[28:29], 0
	v_mov_b64_e32 v[30:31], 0
	v_mov_b64_e32 v[32:33], 0
	v_mov_b64_e32 v[42:43], 0
	v_mov_b64_e32 v[44:45], 0
	v_mov_b64_e32 v[46:47], 0
	v_mov_b64_e32 v[48:49], 0
	v_mov_b64_e32 v[58:59], 0
	v_mov_b64_e32 v[60:61], 0
	v_mov_b64_e32 v[62:63], 0
	v_mov_b64_e32 v[64:65], 0
	v_mov_b64_e32 v[66:67], 0
	v_mov_b64_e32 v[68:69], 0
	v_mov_b64_e32 v[70:71], 0
	v_mov_b64_e32 v[72:73], 0
	v_mov_b64_e32 v[82:83], 0
	v_mov_b64_e32 v[84:85], 0
	s_waitcnt vmcnt(0)
	v_mov_b64_e32 v[86:87], 0
	v_mov_b64_e32 v[88:89], 0
	v_mov_b64_e32 v[98:99], 0
	v_mov_b64_e32 v[100:101], 0
	v_mov_b64_e32 v[102:103], 0
	v_mov_b64_e32 v[104:105], 0
	v_mov_b64_e32 v[114:115], 0
	v_mov_b64_e32 v[116:117], 0
	v_mov_b64_e32 v[118:119], 0
	v_mov_b64_e32 v[120:121], 0
	v_mov_b64_e32 v[74:75], 0
	v_mov_b64_e32 v[76:77], 0
	v_mov_b64_e32 v[78:79], 0
	v_mov_b64_e32 v[80:81], 0
	v_mov_b64_e32 v[90:91], 0
	v_mov_b64_e32 v[92:93], 0
	v_mov_b64_e32 v[94:95], 0
	v_mov_b64_e32 v[96:97], 0
	v_mov_b64_e32 v[106:107], 0
	v_mov_b64_e32 v[108:109], 0
	v_mov_b64_e32 v[110:111], 0
	v_mov_b64_e32 v[112:113], 0
	v_mov_b64_e32 v[122:123], 0
	v_mov_b64_e32 v[124:125], 0
	v_mov_b64_e32 v[126:127], 0
	v_mov_b64_e32 v[128:129], 0
